# DN chunk token bookkeeping strength-reduced: tok0 advanced by +-16 per chunk, original computation kept out of line for the first chunk and the context->latent switch
# speedup vs baseline: 1.0086x; 1.0086x over previous
.Ldn_tok_ctx:
	s_lshl_b32 s6, s4, 4
	v_readlane_b32 s8, v254, 7
	s_sub_i32 s2, 0xff, s6
	v_readlane_b32 s9, v254, 8
	s_and_b64 s[10:11], s[8:9], exec
	s_cselect_b32 s2, s6, s2
	v_readlane_b32 s3, v254, 5
	s_or_b32 s18, s2, s3
	s_branch .LBB0_904
.Ldn_tok_lat:
	s_lshl_b32 s6, s4, 4
	v_readlane_b32 s8, v254, 7
	s_sub_i32 s2, 0x8ff, s6
	s_add_i32 s3, s6, 0xffffff00
	v_readlane_b32 s9, v254, 8
	s_and_b64 s[10:11], s[8:9], exec
	s_cselect_b32 s2, s3, s2
	v_readlane_b32 s3, v254, 10
	s_add_i32 s18, s2, s3
	s_branch .LBB0_904

.LBB0_900:
	ds_read_b128 v[30:33], v94
	ds_read_b128 v[26:29], v94 offset:16
	ds_read_b128 v[22:25], v94 offset:32
	ds_read_b128 v[18:21], v94 offset:48
	ds_read_b128 v[2:5], v94 offset:256
	ds_read_b128 v[6:9], v94 offset:272
	ds_read_b32 v73, v95 offset:512
	ds_read_b128 v[34:37], v1 offset:768
	ds_read_b128 v[14:17], v94 offset:288
	ds_read_b128 v[10:13], v94 offset:304
	s_cmp_lg_u32 s4, 0
	s_cbranch_scc0 .Ldn_tok_ctx
	s_cmp_lg_u32 s4, 16
	s_cbranch_scc0 .Ldn_tok_lat
	s_lshl_b32 s2, s24, 5
	s_add_i32 s18, s18, s2

.LBB0_910:
	s_waitcnt lgkmcnt(0)
	s_barrier
	ds_read_b128 v[30:33], v94 offset:12800
	ds_read_b128 v[26:29], v94 offset:12816
	ds_read_b128 v[22:25], v94 offset:12832
	ds_read_b128 v[18:21], v94 offset:12848
	ds_read_b128 v[2:5], v94 offset:13056
	ds_read_b128 v[6:9], v94 offset:13072
	ds_read_b32 v73, v95 offset:13312
	ds_read_b128 v[34:37], v1 offset:13568
	ds_read_b128 v[14:17], v94 offset:13088
	ds_read_b128 v[10:13], v94 offset:13104
	s_lshl_b32 s2, s24, 4
	s_add_i32 s16, s18, s2
